# final candidate: v16 plus SGPR-base form prefetch loads in the MLA loop and compute-dtype header comment
# speedup vs baseline: 1.0333x; 1.0021x over previous
; DI int tid() { int t = threadIdx.x; asm volatile("" : "+v"(t)); return t; }
; #define M2_STORE(S, buf) { M2_SK(0, S##k0, buf) M2_SK(1, S##k1, buf) M2_SK(2, S##k2, buf) M2_SV(0, S##v0, buf) M2_SV(1, S##v1, buf) }
; DI void flash_mla2(const bf16_t* __restrict__ Qp, const bf16_t* __restrict__ Kp, const bf16_t* __restrict__ Vtp,
;                    bf16_t* __restrict__ Op, char* smem, float& ssq) {
;     ...
;     const int t = tid(), lane = t & 63, w = __builtin_amdgcn_readfirstlane(t >> 6), l32 = lane & 31, h = lane >> 5;
;     const int q = w * 32 + l32;
;     const unsigned ktoff = (unsigned)(t * 8);
;     const unsigned vtoff = (unsigned)((t >> 3) * LDV + (t & 7) * 8);
;     bf16x8 qf[NKS];
; #pragma unroll
;     for (int ks = 0; ks < NKS; ++ks) qf[ks] = *(const bf16x8*)(Qp + (size_t)q * LDQ + ks * 16 + 8 * h);
;     f32x16 o[NMT];
; #pragma unroll
;     for (int mt = 0; mt < NMT; ++mt)
; #pragma unroll
;         for (int r = 0; r < 16; ++r) o[mt][r] = 0.f;
;     float m = 0.f, lsum = 0.f;
;     uint4 ak0, ak1, ak2, av0, av1, bk0, bk1, bk2, bv0, bv1;
;     ...
;     float alpha = 1.f;
;     __syncthreads();
;     M2_LOAD(a, 0);
;     M2_LOAD(b, 1);
;     {
;         M2_STORE(a, 0);
;         __syncthreads();
.LBB0_182:
	s_add_i32 s18, s34, s13
	s_ashr_i32 s19, s18, 31
	s_lshl_b64 s[16:17], s[18:19], 13
	s_or_b32 s16, s16, s12
	s_mulk_i32 s17, 0xc0
	s_mul_hi_u32 s35, s16, 0xc0
	s_add_i32 s35, s35, s17
	s_mulk_i32 s16, 0xc0
	s_add_u32 s36, s6, s16
	s_addc_u32 s37, s7, s35
	s_mul_i32 s16, s18, 0x180000
	s_mul_hi_i32 s17, s18, 0x180000
	s_add_u32 s16, s8, s16
	s_addc_u32 s17, s9, s17
	s_lshl_b64 s[18:19], s[18:19], 20
	v_mov_b32_e32 v1, v182
	s_add_u32 s18, s10, s18
	s_addc_u32 s19, s11, s19
	v_readfirstlane_b32 s35, v1
	s_ashr_i32 s35, s35, 1
	s_waitcnt vmcnt(1)
	v_bfe_u32 v142, v1, 5, 1
	v_mov_b32_e32 v2, s35
	v_bfi_b32 v132, s80, v2, v1
	v_mov_b64_e32 v[2:3], s[36:37]
	v_mad_i64_i32 v[2:3], s[36:37], v132, s86, v[2:3]
	v_lshlrev_b32_e32 v4, 4, v142
	v_mov_b32_e32 v5, v35
	v_lshlrev_b32_e32 v34, 3, v1
	v_lshl_add_u64 v[2:3], v[2:3], 0, v[4:5]
	global_load_dwordx4 v[68:71], v[2:3], off
	global_load_dwordx4 v[72:75], v[2:3], off offset:32
	global_load_dwordx4 v[76:79], v[2:3], off offset:64
	global_load_dwordx4 v[80:83], v[2:3], off offset:96
	global_load_dwordx4 v[84:87], v[2:3], off offset:128
	global_load_dwordx4 v[88:91], v[2:3], off offset:160
	v_lshl_add_u64 v[2:3], v[34:35], 1, s[16:17]
	v_add_co_u32_e32 v6, vcc, s84, v2
	v_ashrrev_i32_e32 v5, 3, v1
	v_and_b32_e32 v12, 56, v34
	v_addc_co_u32_e32 v7, vcc, 0, v3, vcc
	v_lshl_or_b32 v134, v5, 6, v12
	v_mov_b32_e32 v135, v35
	s_barrier
	global_load_dwordx4 v[92:95], v[2:3], off
	global_load_dwordx4 v[100:103], v[6:7], off offset:-4096
	global_load_dwordx4 v[96:99], v[6:7], off
	v_lshl_add_u64 v[6:7], v[134:135], 1, s[18:19]
	s_mov_b32 s35, 0x1000
	v_add_co_u32_e32 v8, vcc, s35, v6
	global_load_dwordx4 v[104:107], v[6:7], off
	s_nop 0
	v_addc_co_u32_e32 v9, vcc, 0, v7, vcc
	global_load_dwordx4 v[108:111], v[8:9], off
	v_mul_hi_i32 v10, v1, s87
	v_add_u32_e32 v13, 0x100, v1
	v_lshrrev_b32_e32 v11, 31, v10
	v_ashrrev_i32_e32 v10, 1, v10
	v_mul_hi_i32 v14, v13, s87
	v_add_u32_e32 v10, v10, v11
	v_lshrrev_b32_e32 v11, 31, v14
	v_ashrrev_i32_e32 v14, 1, v14
	v_mul_lo_u32 v15, v10, -12
	v_and_b32_e32 v16, 0xffffff3, v10
	v_lshlrev_b32_e32 v17, 1, v10
	v_lshrrev_b32_e32 v10, 1, v10
	v_add_u32_e32 v14, v14, v11
	v_and_b32_e32 v11, 8, v17
	v_and_b32_e32 v10, 4, v10
	v_or3_b32 v10, v11, v16, v10
	v_add_lshl_u32 v15, v15, v1, 4
	v_mul_lo_u32 v10, v10, s88
	s_movk_i32 s35, 0x4000
	s_waitcnt vmcnt(11)
	v_add3_u32 v144, 0, v10, v15
	v_add_co_u32_e32 v10, vcc, s35, v2
	v_lshlrev_b32_e32 v19, 1, v14
	s_nop 0
	v_addc_co_u32_e32 v11, vcc, 0, v3, vcc
	v_add_co_u32_e32 v2, vcc, s83, v2
	v_and_b32_e32 v18, 0xffffff3, v14
	s_nop 0
	v_addc_co_u32_e32 v3, vcc, 0, v3, vcc
	v_add_co_u32_e32 v6, vcc, 0x2000, v6
	s_nop 1
	v_addc_co_u32_e32 v7, vcc, 0, v7, vcc
	v_add_co_u32_e32 v8, vcc, 0x2000, v8
	s_nop 1
	v_addc_co_u32_e32 v9, vcc, 0, v9, vcc
	global_load_dwordx4 v[112:115], v[10:11], off offset:-4096
	global_load_dwordx4 v[116:119], v[10:11], off
	global_load_dwordx4 v[120:123], v[6:7], off
	global_load_dwordx4 v[124:127], v[2:3], off
	global_load_dwordx4 v[128:131], v[8:9], off
	v_lshrrev_b32_e32 v2, 1, v14
	v_and_b32_e32 v16, 8, v19
	v_and_b32_e32 v2, 4, v2
	v_mul_lo_u32 v17, v14, -12
	v_or3_b32 v2, v16, v18, v2
	v_and_b32_e32 v44, 31, v1
	v_mul_lo_u32 v2, v2, s88
	v_add_lshl_u32 v3, v17, v13, 4
	v_add_u32_e32 v1, 0x200, v1
	v_add3_u32 v145, 0, v2, v3
	v_mul_hi_i32 v2, v1, s87
	v_lshrrev_b32_e32 v3, 31, v2
	v_ashrrev_i32_e32 v2, 1, v2
	v_add_u32_e32 v2, v2, v3
	v_mul_lo_u32 v3, v2, -12
	v_and_b32_e32 v6, 0xffffff3, v2
	v_lshlrev_b32_e32 v7, 1, v2
	v_lshrrev_b32_e32 v2, 1, v2
	v_and_b32_e32 v7, 8, v7
	v_and_b32_e32 v2, 4, v2
	v_or3_b32 v2, v7, v6, v2
	v_mul_lo_u32 v2, v2, s88
	v_add_lshl_u32 v1, v3, v1, 4
	v_add3_u32 v146, 0, v2, v1
	v_mul_lo_u32 v1, v5, s81
	v_lshlrev_b32_e32 v2, 1, v12
	v_add3_u32 v147, 0, v1, v2
	v_lshrrev_b32_e32 v1, 3, v13
	v_mul_lo_u32 v1, v1, s81
	v_add3_u32 v148, 0, v1, v2
	v_mul_u32_u24_e32 v1, 0x68, v44
	v_lshlrev_b32_e32 v1, 1, v1
	v_add3_u32 v149, 0, v1, v4
	v_ashrrev_i32_e32 v133, 31, v132
	v_mov_b32_e32 v138, 1.0
	s_mov_b32 s35, -2
	v_mov_b32_e32 v140, 0
	s_waitcnt vmcnt(9)
	ds_write_b128 v144, v[92:95]
	s_waitcnt vmcnt(8)
	ds_write_b128 v145, v[100:103]
	s_waitcnt vmcnt(7)
	ds_write_b128 v146, v[96:99]
	s_waitcnt vmcnt(6)
	ds_write_b128 v147, v[104:107] offset:26624
	s_waitcnt vmcnt(5)
	ds_write_b128 v148, v[108:111] offset:26624
	s_add_u32 s36, s16, 0x6000
	s_addc_u32 s37, s17, 0
	s_mov_b32 s41, 2
	v_lshl_add_u64 v[36:37], v[34:35], 1, s[36:37]
	s_lshl_b32 s36, s41, 13
	global_load_dwordx4 v[92:95], v[36:37], off
	v_add_co_u32_e32 v36, vcc, s84, v36
	s_add_u32 s36, s18, s36
	s_nop 0
	v_addc_co_u32_e32 v37, vcc, 0, v37, vcc
	s_addc_u32 s37, s19, 0
	global_load_dwordx4 v[100:103], v[36:37], off offset:-4096
	global_load_dwordx4 v[96:99], v[36:37], off
	v_lshl_add_u64 v[36:37], v[134:135], 1, s[36:37]
	global_load_dwordx4 v[104:107], v[36:37], off
	v_add_co_u32_e32 v36, vcc, 0x1000, v36
	s_nop 1
	v_addc_co_u32_e32 v37, vcc, 0, v37, vcc
	global_load_dwordx4 v[108:111], v[36:37], off
	s_waitcnt lgkmcnt(0)
	s_barrier
; #define MFMA(a, b, c) __builtin_amdgcn_mfma_f32_32x32x16_bf16((a), (b), (c), 0, 0, 0)
; #define M2_STORE(S, buf) { M2_SK(0, S##k0, buf) M2_SK(1, S##k1, buf) M2_SK(2, S##k2, buf) M2_SV(0, S##v0, buf) M2_SV(1, S##v1, buf) }
; DI void flash_mla2(const bf16_t* __restrict__ Qp, const bf16_t* __restrict__ Kp, const bf16_t* __restrict__ Vtp,
;                    bf16_t* __restrict__ Op, char* smem, float& ssq) {
;     ...
;         const bf16_t* kb = Ks + l32 * KP + 8 * h;
;         f32x16 s0, s1;
; #pragma unroll
;         for (int r = 0; r < 16; ++r) { s0[r] = 0.f; s1[r] = 0.f; }
; #pragma unroll
;         for (int ks = 0; ks < NKS; ++ks) { bf16x8 k0 = *(const bf16x8*)(kb + ks * 16); bf16x8 k1 = *(const bf16x8*)(kb + 32 * KP + ks * 16); s0 = MFMA(k0, qf[ks], s0); s1 = MFMA(k1, qf[ks], s1); }
;         float mx = s0[0];
; #pragma unroll
;         for (int r = 1; r < 16; ++r) mx = fmaxf(mx, s0[r]);
; #pragma unroll
;         for (int r = 0; r < 16; ++r) mx = fmaxf(mx, s1[r]);
;         m = fmaxf(mx, __shfl_xor(mx, 32));
;         __syncthreads();
;     }
;     for (int kt = 0; kt < NKT; kt += 2) {
;         M2_STORE(a, 0);
;         __syncthreads();
;         M2_LOAD(a, min(kt + 2, NKT - 1));
;         M2_COMPUTE(0);
;         M2_STORE(b, 1);
;         __syncthreads();
;         M2_LOAD(b, min(kt + 3, NKT - 1));
	ds_read_b128 v[2:5], v149
	ds_read_b128 v[18:21], v149 offset:32
	s_waitcnt lgkmcnt(1)
	v_mfma_f32_32x32x16_bf16 v[2:17], v[2:5], v[68:71], 0
	s_waitcnt lgkmcnt(0)
	v_mfma_f32_32x32x16_bf16 v[2:17], v[18:21], v[72:75], v[2:17]
	ds_read_b128 v[18:21], v149 offset:64
	ds_read_b128 v[22:25], v149 offset:96
	s_waitcnt lgkmcnt(1)
	v_mfma_f32_32x32x16_bf16 v[2:17], v[18:21], v[76:79], v[2:17]
	s_waitcnt lgkmcnt(0)
	v_mfma_f32_32x32x16_bf16 v[2:17], v[22:25], v[80:83], v[2:17]
	ds_read_b128 v[18:21], v149 offset:128
	ds_read_b128 v[22:25], v149 offset:160
	s_waitcnt lgkmcnt(1)
	v_mfma_f32_32x32x16_bf16 v[2:17], v[18:21], v[84:87], v[2:17]
	ds_read_b128 v[18:21], v149 offset:6656
	ds_read_b128 v[36:39], v149 offset:6688
	s_waitcnt lgkmcnt(2)
	v_mfma_f32_32x32x16_bf16 v[2:17], v[22:25], v[88:91], v[2:17]
	s_waitcnt lgkmcnt(1)
	v_mfma_f32_32x32x16_bf16 v[18:33], v[18:21], v[68:71], 0
	s_nop 9
	v_max_f32_e32 v1, v3, v3
	v_max_f32_e32 v2, v2, v2
	v_max_f32_e32 v1, v2, v1
	v_max3_f32 v1, v1, v4, v5
	v_max3_f32 v1, v1, v6, v7
	v_max3_f32 v1, v1, v8, v9
	v_max3_f32 v1, v1, v10, v11
	s_waitcnt lgkmcnt(0)
	v_mfma_f32_32x32x16_bf16 v[18:33], v[36:39], v[72:75], v[18:33]
	ds_read_b128 v[36:39], v149 offset:6720
	ds_read_b128 v[40:43], v149 offset:6752
	v_max3_f32 v1, v1, v12, v13
	v_max3_f32 v1, v1, v14, v15
	v_max3_f32 v1, v1, v16, v17
	v_xor_b32_e32 v2, 32, v184
	v_cmp_lt_i32_e32 vcc, v2, v187
	v_mov_b32_e32 v3, v0
	s_waitcnt lgkmcnt(1)
	v_mfma_f32_32x32x16_bf16 v[18:33], v[36:39], v[76:79], v[18:33]
	v_cndmask_b32_e32 v2, v184, v2, vcc
	v_lshlrev_b32_e32 v143, 2, v2
	v_mov_b32_e32 v4, v0
	v_mov_b32_e32 v5, v0
	v_mov_b32_e32 v6, v0
	v_mov_b32_e32 v7, v0
	v_mov_b32_e32 v8, v0
	s_waitcnt lgkmcnt(0)
	v_mfma_f32_32x32x16_bf16 v[18:33], v[40:43], v[80:83], v[18:33]
	ds_read_b128 v[36:39], v149 offset:6784
	ds_read_b128 v[40:43], v149 offset:6816
	v_mov_b32_e32 v9, v0
	v_mov_b32_e32 v10, v0
	v_mov_b32_e32 v11, v0
	v_mov_b32_e32 v12, v0
	v_mov_b32_e32 v13, v0
	v_mov_b32_e32 v14, v0
	s_waitcnt lgkmcnt(1)
	v_mfma_f32_32x32x16_bf16 v[18:33], v[36:39], v[84:87], v[18:33]
	v_mov_b32_e32 v15, v0
	v_mov_b32_e32 v16, v0
	v_mov_b32_e32 v17, v0
	s_waitcnt lgkmcnt(0)
	s_barrier
	v_mfma_f32_32x32x16_bf16 v[18:33], v[40:43], v[88:91], v[18:33]
	s_nop 11
	v_max3_f32 v1, v1, v18, v19
	v_max3_f32 v1, v1, v20, v21
	v_max3_f32 v1, v1, v22, v23
	v_max3_f32 v1, v1, v24, v25
	v_max3_f32 v1, v1, v26, v27
	v_max3_f32 v1, v1, v28, v29
	v_max3_f32 v1, v1, v30, v31
	v_max3_f32 v1, v1, v32, v33
	ds_bpermute_b32 v2, v143, v1
	v_mov_b32_e32 v18, v0
	v_mov_b32_e32 v19, v0
	v_mov_b32_e32 v20, v0
	v_mov_b32_e32 v21, v0
	s_waitcnt lgkmcnt(0)
	v_max_f32_e32 v2, v2, v2
	v_max_f32_e32 v141, v1, v2
	v_lshlrev_b32_e32 v1, 6, v44
	v_mov_b32_e32 v2, v0
	v_mov_b32_e32 v22, v0
	v_mov_b32_e32 v23, v0
	v_mov_b32_e32 v24, v0
	v_mov_b32_e32 v25, v0
	v_mov_b32_e32 v26, v0
	v_mov_b32_e32 v27, v0
	v_mov_b32_e32 v28, v0
	v_mov_b32_e32 v29, v0
	v_mov_b32_e32 v30, v0
	v_mov_b32_e32 v31, v0
	v_sub_u32_e32 v150, v149, v1
	v_mov_b32_e32 v1, v0
	v_mov_b64_e32 v[32:33], v[30:31]
	v_mov_b64_e32 v[30:31], v[28:29]
	v_mov_b64_e32 v[28:29], v[26:27]
	v_mov_b64_e32 v[26:27], v[24:25]
	v_mov_b64_e32 v[24:25], v[22:23]
	v_mov_b64_e32 v[22:23], v[20:21]
	v_mov_b64_e32 v[20:21], v[18:19]
	v_mov_b64_e32 v[18:19], v[16:17]
	v_mov_b64_e32 v[16:17], v[14:15]
	v_mov_b64_e32 v[14:15], v[12:13]
	v_mov_b64_e32 v[12:13], v[10:11]
	v_mov_b64_e32 v[10:11], v[8:9]
	v_mov_b64_e32 v[8:9], v[6:7]
	v_mov_b64_e32 v[6:7], v[4:5]
	v_mov_b64_e32 v[4:5], v[2:3]
	v_mov_b64_e32 v[2:3], v[0:1]
	v_lshlrev_b32_e32 v136, 1, v34
	v_lshlrev_b32_e32 v151, 1, v134
	v_add_u32_e32 v137, 0x2000, v136
	v_xor_b32_e32 v179, 0x80000000, v141
	v_mov_b32_e32 v232, v179
	v_mov_b32_e32 v233, v179
	v_mov_b32_e32 v234, v179
	v_mov_b32_e32 v235, v179
	v_mov_b32_e32 v236, v179
	v_mov_b32_e32 v237, v179
	v_mov_b32_e32 v238, v179
	v_mov_b32_e32 v239, v179
	v_mov_b32_e32 v240, v179
	v_mov_b32_e32 v241, v179
	v_mov_b32_e32 v242, v179
	v_mov_b32_e32 v243, v179
	v_mov_b32_e32 v244, v179
	v_mov_b32_e32 v245, v179
	v_mov_b32_e32 v246, v179
	v_mov_b32_e32 v247, v179
	s_branch .LBB0_184
.LBB0_184:
	s_add_i32 s35, s35, 2
	s_min_u32 s36, s35, 0x7c
	s_add_i32 s41, s36, 3
	s_mul_i32 s36, s41, 0x3000
	s_add_u32 s36, s16, s36
	s_addc_u32 s37, s17, 0
	s_waitcnt lgkmcnt(0)
	s_barrier
	s_waitcnt vmcnt(9)
	ds_write_b128 v144, v[112:115] offset:13312
	s_waitcnt vmcnt(8)
	ds_write_b128 v145, v[116:119] offset:13312
	s_waitcnt vmcnt(6)
	ds_write_b128 v146, v[124:127] offset:13312
	ds_write_b128 v147, v[120:123] offset:35840
	s_waitcnt vmcnt(5)
	ds_write_b128 v148, v[128:131] offset:35840
	global_load_dwordx4 v[112:115], v136, s[36:37]
	global_load_dwordx4 v[116:119], v137, s[36:37] offset:-4096
	global_load_dwordx4 v[124:127], v137, s[36:37]
	s_lshl_b32 s36, s41, 13
	s_add_u32 s36, s18, s36
	s_addc_u32 s37, s19, 0
	s_add_u32 s36, s36, 0x800
	s_addc_u32 s37, s37, 0
	global_load_dwordx4 v[120:123], v151, s[36:37] offset:-2048
	global_load_dwordx4 v[128:131], v151, s[36:37] offset:2048
	v_cmp_neq_f32_e32 vcc, 1.0, v138
	s_cbranch_vccz .Lmla_c0
	v_pk_mul_f32 v[32:33], v[138:139], v[32:33] op_sel_hi:[0,1]
	v_pk_mul_f32 v[30:31], v[138:139], v[30:31] op_sel_hi:[0,1]
	v_pk_mul_f32 v[28:29], v[138:139], v[28:29] op_sel_hi:[0,1]
	v_pk_mul_f32 v[26:27], v[138:139], v[26:27] op_sel_hi:[0,1]
	v_pk_mul_f32 v[24:25], v[138:139], v[24:25] op_sel_hi:[0,1]
	v_pk_mul_f32 v[22:23], v[138:139], v[22:23] op_sel_hi:[0,1]
	v_pk_mul_f32 v[20:21], v[138:139], v[20:21] op_sel_hi:[0,1]
	v_pk_mul_f32 v[18:19], v[138:139], v[18:19] op_sel_hi:[0,1]
	v_pk_mul_f32 v[16:17], v[138:139], v[16:17] op_sel_hi:[0,1]
	v_pk_mul_f32 v[14:15], v[138:139], v[14:15] op_sel_hi:[0,1]
	v_pk_mul_f32 v[12:13], v[138:139], v[12:13] op_sel_hi:[0,1]
	v_pk_mul_f32 v[10:11], v[138:139], v[10:11] op_sel_hi:[0,1]
	v_pk_mul_f32 v[8:9], v[138:139], v[8:9] op_sel_hi:[0,1]
	v_pk_mul_f32 v[6:7], v[138:139], v[6:7] op_sel_hi:[0,1]
	v_pk_mul_f32 v[4:5], v[138:139], v[4:5] op_sel_hi:[0,1]
	v_pk_mul_f32 v[2:3], v[138:139], v[2:3] op_sel_hi:[0,1]
	v_xor_b32_e32 v179, 0x80000000, v141
	v_mov_b32_e32 v232, v179
	v_mov_b32_e32 v233, v179
	v_mov_b32_e32 v234, v179
	v_mov_b32_e32 v235, v179
	v_mov_b32_e32 v236, v179
	v_mov_b32_e32 v237, v179
	v_mov_b32_e32 v238, v179
	v_mov_b32_e32 v239, v179
	v_mov_b32_e32 v240, v179
	v_mov_b32_e32 v241, v179
	v_mov_b32_e32 v242, v179
	v_mov_b32_e32 v243, v179
	v_mov_b32_e32 v244, v179
	v_mov_b32_e32 v245, v179
	v_mov_b32_e32 v246, v179
	v_mov_b32_e32 v247, v179
.Lmla_c0:
	ds_read_b128 v[152:155], v149
	ds_read_b128 v[156:159], v149 offset:32
	ds_read_b128 v[160:163], v149 offset:64
	ds_read_b128 v[164:167], v149 offset:96
	ds_read_b128 v[168:171], v149 offset:128
	ds_read_b128 v[172:175], v149 offset:160
	s_waitcnt lgkmcnt(5)
	v_mfma_f32_32x32x16_bf16 v[52:67], v[152:155], v[68:71], v[232:247]
	ds_read_b128 v[152:155], v149 offset:6656
	s_waitcnt lgkmcnt(5)
	v_mfma_f32_32x32x16_bf16 v[52:67], v[156:159], v[72:75], v[52:67]
	ds_read_b128 v[156:159], v149 offset:6688
	s_waitcnt lgkmcnt(5)
	v_mfma_f32_32x32x16_bf16 v[52:67], v[160:163], v[76:79], v[52:67]
	ds_read_b128 v[160:163], v149 offset:6720
	s_waitcnt lgkmcnt(5)
	v_mfma_f32_32x32x16_bf16 v[52:67], v[164:167], v[80:83], v[52:67]
	ds_read_b128 v[164:167], v149 offset:6752
	s_waitcnt lgkmcnt(5)
	v_mfma_f32_32x32x16_bf16 v[52:67], v[168:171], v[84:87], v[52:67]
	ds_read_b128 v[168:171], v149 offset:6784
	ds_read_b128 v[198:201], v150 offset:26624
	s_waitcnt lgkmcnt(6)
	v_mfma_f32_32x32x16_bf16 v[52:67], v[172:175], v[88:91], v[52:67]
	ds_read_b128 v[172:175], v149 offset:6816
	ds_read_b128 v[202:205], v150 offset:26656
	ds_read_b128 v[206:209], v150 offset:31232
	ds_read_b128 v[210:213], v150 offset:31264
	s_waitcnt lgkmcnt(9)
	v_mfma_f32_32x32x16_bf16 v[36:51], v[152:155], v[68:71], v[232:247]
	s_waitcnt lgkmcnt(8)
	v_mfma_f32_32x32x16_bf16 v[36:51], v[156:159], v[72:75], v[36:51]
	s_nop 3
	v_max3_f32 v178, v52, v53, v54
	v_max3_f32 v178, v178, v55, v56
	v_max3_f32 v178, v178, v57, v58
	v_max3_f32 v178, v178, v59, v60
	v_max3_f32 v178, v178, v61, v62
	v_max3_f32 v178, v178, v63, v64
	v_max3_f32 v178, v178, v65, v66
	v_max_f32_e32 v178, v178, v67
	v_exp_f32_e32 v52, v52
	v_exp_f32_e32 v53, v53
	s_waitcnt lgkmcnt(7)
	v_mfma_f32_32x32x16_bf16 v[36:51], v[160:163], v[76:79], v[36:51]
	v_exp_f32_e32 v54, v54
	v_exp_f32_e32 v55, v55
	v_exp_f32_e32 v56, v56
	v_exp_f32_e32 v57, v57
	v_exp_f32_e32 v58, v58
	v_exp_f32_e32 v59, v59
	s_waitcnt lgkmcnt(6)
	v_mfma_f32_32x32x16_bf16 v[36:51], v[164:167], v[80:83], v[36:51]
	v_exp_f32_e32 v60, v60
	v_exp_f32_e32 v61, v61
	v_exp_f32_e32 v62, v62
	v_exp_f32_e32 v63, v63
	v_exp_f32_e32 v64, v64
	v_exp_f32_e32 v65, v65
	s_waitcnt lgkmcnt(5)
	v_mfma_f32_32x32x16_bf16 v[36:51], v[168:171], v[84:87], v[36:51]
	v_exp_f32_e32 v66, v66
	v_exp_f32_e32 v67, v67
	v_add_f32_e32 v176, v52, v53
	v_add_f32_e32 v176, v54, v176
	v_add_f32_e32 v176, v55, v176
	v_add_f32_e32 v176, v56, v176
	v_add_f32_e32 v176, v57, v176
	v_add_f32_e32 v176, v58, v176
	v_add_f32_e32 v176, v59, v176
	s_waitcnt lgkmcnt(3)
	v_mfma_f32_32x32x16_bf16 v[36:51], v[172:175], v[88:91], v[36:51]
	v_add_f32_e32 v176, v60, v176
	v_add_f32_e32 v176, v61, v176
	v_add_f32_e32 v176, v62, v176
	v_add_f32_e32 v176, v63, v176
	v_add_f32_e32 v176, v64, v176
	v_add_f32_e32 v176, v65, v176
	v_add_f32_e32 v176, v66, v176
	v_add_f32_e32 v176, v67, v176
	v_cvt_pk_bf16_f32 v214, v52, v53
	v_cvt_pk_bf16_f32 v215, v54, v55
	v_cvt_pk_bf16_f32 v216, v56, v57
	v_cvt_pk_bf16_f32 v217, v58, v59
	v_cvt_pk_bf16_f32 v218, v60, v61
	v_cvt_pk_bf16_f32 v219, v62, v63
	v_cvt_pk_bf16_f32 v220, v64, v65
	v_cvt_pk_bf16_f32 v221, v66, v67
	v_mfma_f32_32x32x16_bf16 v[2:17], v[198:201], v[214:217], v[2:17]
	ds_read_b128 v[198:201], v150 offset:26688
	v_max3_f32 v178, v178, v36, v37
	v_max3_f32 v178, v178, v38, v39
	v_max3_f32 v178, v178, v40, v41
	v_max3_f32 v178, v178, v42, v43
	v_max3_f32 v178, v178, v44, v45
	v_max3_f32 v178, v178, v46, v47
	v_max3_f32 v178, v178, v48, v49
	v_max3_f32 v178, v178, v50, v51
	ds_bpermute_b32 v180, v143, v178
	s_waitcnt lgkmcnt(3)
	v_mfma_f32_32x32x16_bf16 v[18:33], v[206:209], v[214:217], v[18:33]
	ds_read_b128 v[206:209], v150 offset:31296
	v_exp_f32_e32 v36, v36
	v_exp_f32_e32 v37, v37
	v_exp_f32_e32 v38, v38
	v_exp_f32_e32 v39, v39
	v_exp_f32_e32 v40, v40
	v_exp_f32_e32 v41, v41
	v_mfma_f32_32x32x16_bf16 v[2:17], v[202:205], v[218:221], v[2:17]
	ds_read_b128 v[202:205], v150 offset:26720
	v_exp_f32_e32 v42, v42
	v_exp_f32_e32 v43, v43
	v_exp_f32_e32 v44, v44
	v_exp_f32_e32 v45, v45
	v_exp_f32_e32 v46, v46
	v_exp_f32_e32 v47, v47
	s_waitcnt lgkmcnt(4)
	v_mfma_f32_32x32x16_bf16 v[18:33], v[210:213], v[218:221], v[18:33]
	ds_read_b128 v[210:213], v150 offset:31328
	v_exp_f32_e32 v48, v48
	v_exp_f32_e32 v49, v49
	v_exp_f32_e32 v50, v50
	v_exp_f32_e32 v51, v51
	v_cvt_pk_bf16_f32 v222, v36, v37
	v_cvt_pk_bf16_f32 v223, v38, v39
	v_cvt_pk_bf16_f32 v224, v40, v41
	v_cvt_pk_bf16_f32 v225, v42, v43
	v_add_f32_e32 v177, v36, v37
	v_add_f32_e32 v177, v38, v177
	s_waitcnt lgkmcnt(4)
	v_mfma_f32_32x32x16_bf16 v[2:17], v[198:201], v[222:225], v[2:17]
	v_add_f32_e32 v177, v39, v177
	v_add_f32_e32 v177, v40, v177
	v_add_f32_e32 v177, v41, v177
	v_add_f32_e32 v177, v42, v177
	v_add_f32_e32 v177, v43, v177
	v_add_f32_e32 v177, v44, v177
	s_waitcnt lgkmcnt(2)
	v_mfma_f32_32x32x16_bf16 v[18:33], v[206:209], v[222:225], v[18:33]
	v_add_f32_e32 v177, v45, v177
	v_add_f32_e32 v177, v46, v177
	v_add_f32_e32 v177, v47, v177
	v_add_f32_e32 v177, v48, v177
	v_add_f32_e32 v177, v49, v177
	v_add_f32_e32 v177, v50, v177
	v_add_f32_e32 v177, v51, v177
	v_cvt_pk_bf16_f32 v226, v44, v45
	v_cvt_pk_bf16_f32 v227, v46, v47
	v_cvt_pk_bf16_f32 v228, v48, v49
	v_cvt_pk_bf16_f32 v229, v50, v51
	v_max_f32_e32 v180, v178, v180
	v_cmp_lt_f32_e32 vcc, 0x41000000, v180
	v_add_f32_e32 v176, v176, v177
	s_nop 0
	v_cndmask_b32_e32 v181, 0, v180, vcc
	s_waitcnt lgkmcnt(1)
	v_mfma_f32_32x32x16_bf16 v[2:17], v[202:205], v[226:229], v[2:17]
	v_fma_f32 v140, v140, v138, v176
	v_add_f32_e32 v141, v141, v181
	s_waitcnt lgkmcnt(0)
	v_mfma_f32_32x32x16_bf16 v[18:33], v[210:213], v[226:229], v[18:33]
	v_exp_f32_e64 v138, -v181
	s_add_i32 s36, s35, 4
	s_min_u32 s41, s36, 0x7f
	s_mul_i32 s36, s41, 0x3000
	s_add_u32 s36, s16, s36
	s_addc_u32 s37, s17, 0
	s_waitcnt lgkmcnt(0)
	s_barrier
; #define M2_STORE(S, buf) { M2_SK(0, S##k0, buf) M2_SK(1, S##k1, buf) M2_SK(2, S##k2, buf) M2_SV(0, S##v0, buf) M2_SV(1, S##v1, buf) }
; DI void flash_mla2(const bf16_t* __restrict__ Qp, const bf16_t* __restrict__ Kp, const bf16_t* __restrict__ Vtp,
;                    bf16_t* __restrict__ Op, char* smem, float& ssq) {
;     ...
;         M2_STORE(a, 0);
;         __syncthreads();
;         M2_LOAD(a, min(kt + 2, NKT - 1));
;         M2_COMPUTE(0);
;         M2_STORE(b, 1);
;         __syncthreads();
;         M2_LOAD(b, min(kt + 3, NKT - 1));
;         M2_COMPUTE(1);
	s_waitcnt vmcnt(9)
	ds_write_b128 v144, v[92:95]
	s_waitcnt vmcnt(8)
	ds_write_b128 v145, v[100:103]
	s_waitcnt vmcnt(6)
	ds_write_b128 v146, v[96:99]
	ds_write_b128 v147, v[104:107] offset:26624
	s_waitcnt vmcnt(5)
	ds_write_b128 v148, v[108:111] offset:26624
	global_load_dwordx4 v[92:95], v136, s[36:37]
	global_load_dwordx4 v[100:103], v137, s[36:37] offset:-4096
	global_load_dwordx4 v[96:99], v137, s[36:37]
	s_lshl_b32 s36, s41, 13
	s_add_u32 s36, s18, s36
	s_addc_u32 s37, s19, 0
	s_add_u32 s36, s36, 0x800
	s_addc_u32 s37, s37, 0
	global_load_dwordx4 v[104:107], v151, s[36:37] offset:-2048
	global_load_dwordx4 v[108:111], v151, s[36:37] offset:2048
	v_cmp_neq_f32_e32 vcc, 1.0, v138
	s_cbranch_vccz .Lmla_c1
	v_pk_mul_f32 v[32:33], v[138:139], v[32:33] op_sel_hi:[0,1]
	v_pk_mul_f32 v[30:31], v[138:139], v[30:31] op_sel_hi:[0,1]
	v_pk_mul_f32 v[28:29], v[138:139], v[28:29] op_sel_hi:[0,1]
	v_pk_mul_f32 v[26:27], v[138:139], v[26:27] op_sel_hi:[0,1]
	v_pk_mul_f32 v[24:25], v[138:139], v[24:25] op_sel_hi:[0,1]
	v_pk_mul_f32 v[22:23], v[138:139], v[22:23] op_sel_hi:[0,1]
	v_pk_mul_f32 v[20:21], v[138:139], v[20:21] op_sel_hi:[0,1]
	v_pk_mul_f32 v[18:19], v[138:139], v[18:19] op_sel_hi:[0,1]
	v_pk_mul_f32 v[16:17], v[138:139], v[16:17] op_sel_hi:[0,1]
	v_pk_mul_f32 v[14:15], v[138:139], v[14:15] op_sel_hi:[0,1]
	v_pk_mul_f32 v[12:13], v[138:139], v[12:13] op_sel_hi:[0,1]
	v_pk_mul_f32 v[10:11], v[138:139], v[10:11] op_sel_hi:[0,1]
	v_pk_mul_f32 v[8:9], v[138:139], v[8:9] op_sel_hi:[0,1]
	v_pk_mul_f32 v[6:7], v[138:139], v[6:7] op_sel_hi:[0,1]
	v_pk_mul_f32 v[4:5], v[138:139], v[4:5] op_sel_hi:[0,1]
	v_pk_mul_f32 v[2:3], v[138:139], v[2:3] op_sel_hi:[0,1]
	v_xor_b32_e32 v179, 0x80000000, v141
	v_mov_b32_e32 v232, v179
	v_mov_b32_e32 v233, v179
	v_mov_b32_e32 v234, v179
	v_mov_b32_e32 v235, v179
	v_mov_b32_e32 v236, v179
	v_mov_b32_e32 v237, v179
	v_mov_b32_e32 v238, v179
	v_mov_b32_e32 v239, v179
	v_mov_b32_e32 v240, v179
	v_mov_b32_e32 v241, v179
	v_mov_b32_e32 v242, v179
	v_mov_b32_e32 v243, v179
	v_mov_b32_e32 v244, v179
	v_mov_b32_e32 v245, v179
	v_mov_b32_e32 v246, v179
	v_mov_b32_e32 v247, v179
